# LoRA A/decay GEMM epilogues: bias vectors loaded once per tile instead of 8 reload+vmcnt(0) groups that also waited on the previous store
# speedup vs baseline: 1.0101x; 1.0008x over previous
; template <class Epi>
; DI void gemm_small(const u16* __restrict__ A, int lda, const u16* __restrict__ Bt, int ldb, int N, int K, u16* __restrict__ O, int ldo, Epi epi,
;                    char* smem, int& rot) {
;     ...
;   for (int tile = first; tile < ntiles; tile += gridDim.x) {
;     const int grp = tile / (8 * NT), rem = tile - grp * 8 * NT;
;     const int mt = grp * 8 + (rem & 7), nt = rem >> 3;
;     const int m0 = mt << 8, n0 = nt << 7;
;     const u16* Ap = A + (size_t)(m0 + ldrow) * lda + ldkc * 8;
;     const u16* Bp = Bt + (size_t)(n0 + (ldrow & ~31) + pg8::perm32(ldrow & 31)) * ldb + ldkc * 8;
;     uint4 ra0 = *(const uint4*)Ap, ra1 = *(const uint4*)(Ap + (size_t)128 * lda);
;     uint4 rb0 = *(const uint4*)Bp;
;     f32x4 acc[4][4];
; #pragma unroll
;     for (int i = 0; i < 4; ++i)
; #pragma unroll
;       for (int j = 0; j < 4; ++j) acc[i][j] = (f32x4){0.f, 0.f, 0.f, 0.f};
;     *(uint4*)(sA + ldrow * 48 + ldkc * 8) = ra0;
;     *(uint4*)(sA + (ldrow + 128) * 48 + ldkc * 8) = ra1;
;     *(uint4*)(sB + ldrow * 48 + ldkc * 8) = rb0;
;     __syncthreads();
;     for (int kt = 0; kt < KT; ++kt) {
;       const int cur = kt & 1;
;       if (kt + 1 < KT) {
;         const int ko = (kt + 1) << 5;
;         ra0 = *(const uint4*)(Ap + ko); ra1 = *(const uint4*)(Ap + (size_t)128 * lda + ko);
;         rb0 = *(const uint4*)(Bp + ko);
;       }
;       const u16* as = sA + cur * 256 * 48 + (wm * 64 + r16) * 48 + quad * 8;
;       const u16* bs = sB + cur * 128 * 48 + (wn * 64 + r16) * 48 + quad * 8;
;       bf16x8 af[4], bfr[4];
; #pragma unroll
;       for (int i = 0; i < 4; ++i) { af[i] = *(const bf16x8*)(as + i * 16 * 48); bfr[i] = *(const bf16x8*)(bs + i * 16 * 48); }
; #pragma unroll
;       for (int mi = 0; mi < 4; ++mi)
; #pragma unroll
;         for (int ni = 0; ni < 4; ++ni) acc[mi][ni] = MFMA16(bfr[ni], af[mi], acc[mi][ni]);
;       if (kt + 1 < KT) {
;         u16* a2 = sA + (cur ^ 1) * 256 * 48; u16* b2 = sB + (cur ^ 1) * 128 * 48;
;         *(uint4*)(a2 + ldrow * 48 + ldkc * 8) = ra0;
;         *(uint4*)(a2 + (ldrow + 128) * 48 + ldkc * 8) = ra1;
;         *(uint4*)(b2 + ldrow * 48 + ldkc * 8) = rb0;
;       }
;       __syncthreads();
;     }
; #pragma unroll
;     for (int mi = 0; mi < 4; ++mi) {
; #pragma unroll
;       for (int np = 0; np < 2; ++np) {
;         const int m = m0 + wm * 64 + mi * 16 + r16;
.LBB0_1165:
	s_ashr_i32 s0, s26, 31
	s_lshr_b32 s0, s0, 27
	s_add_i32 s0, s26, s0
	s_ashr_i32 s1, s0, 5
	s_lshl_b32 s0, s1, 11
	s_and_b32 s38, s34, 0x700
	s_lshl_b32 s1, s1, 9
	s_or_b32 s0, s0, s38
	s_sub_i32 s1, s33, s1
	s_and_b32 s1, s1, 0xffffff80
	v_add_u32_e32 v2, s0, v1
	v_mad_i64_i32 v[50:51], s[38:39], v2, s9, v[66:67]
	v_add_u32_e32 v2, s1, v76
	v_ashrrev_i32_e32 v3, 31, v2
	v_add_co_u32_e32 v54, vcc, s18, v50
	v_lshlrev_b64 v[2:3], 7, v[2:3]
	s_nop 0
	v_addc_co_u32_e32 v55, vcc, 0, v51, vcc
	v_lshl_add_u64 v[58:59], v[68:69], 0, v[2:3]
	global_load_dwordx4 v[2:5], v[50:51], off
	global_load_dwordx4 v[6:9], v[54:55], off
	global_load_dwordx4 v[10:13], v[58:59], off
	s_waitcnt vmcnt(2)
	ds_write_b128 v77, v[2:5]
	s_waitcnt vmcnt(1)
	ds_write_b128 v77, v[6:9] offset:12288
	s_waitcnt vmcnt(0)
	ds_write_b128 v77, v[10:13] offset:49152
	s_waitcnt lgkmcnt(0)
	s_barrier
	ds_read_b128 v[2:5], v80 offset:49152
	ds_read_b128 v[6:9], v79
	ds_read_b128 v[14:17], v80 offset:50688
	ds_read_b128 v[22:25], v80 offset:52224
	ds_read_b128 v[30:33], v80 offset:53760
	ds_read_b128 v[34:37], v79 offset:1536
	ds_read_b128 v[46:49], v79 offset:3072
	s_waitcnt lgkmcnt(0)
	v_mfma_f32_16x16x32_bf16 v[84:87], v[2:5], v[46:49], 0
	v_mfma_f32_16x16x32_bf16 v[88:91], v[14:17], v[46:49], 0
	v_mfma_f32_16x16x32_bf16 v[92:95], v[22:25], v[46:49], 0
	v_mfma_f32_16x16x32_bf16 v[96:99], v[30:33], v[46:49], 0
	ds_read_b128 v[46:49], v79 offset:4608
	global_load_dwordx4 v[50:53], v[50:51], off offset:64
	s_nop 0
	global_load_dwordx4 v[54:57], v[54:55], off offset:64
	v_mfma_f32_16x16x32_bf16 v[18:21], v[14:17], v[6:9], 0
	v_mfma_f32_16x16x32_bf16 v[42:45], v[14:17], v[34:37], 0
	s_waitcnt lgkmcnt(0)
	v_mfma_f32_16x16x32_bf16 v[100:103], v[14:17], v[46:49], 0
	global_load_dwordx4 v[14:17], v[58:59], off offset:64
	s_waitcnt vmcnt(2)
	ds_write_b128 v77, v[50:53] offset:24576
	s_waitcnt vmcnt(1)
	ds_write_b128 v77, v[54:57] offset:36864
	s_waitcnt vmcnt(0)
	ds_write_b128 v77, v[14:17] offset:61440
	s_waitcnt lgkmcnt(0)
	s_barrier
	ds_read_b128 v[14:17], v80 offset:61440
	v_mfma_f32_16x16x32_bf16 v[26:29], v[22:25], v[6:9], 0
	ds_read_b128 v[112:115], v80 offset:64512
	ds_read_b128 v[116:119], v81 offset:16896
	v_mfma_f32_16x16x32_bf16 v[70:73], v[22:25], v[34:37], 0
	v_mfma_f32_16x16x32_bf16 v[104:107], v[22:25], v[46:49], 0
	ds_read_b128 v[22:25], v79 offset:24576
	v_mfma_f32_16x16x32_bf16 v[10:13], v[2:5], v[6:9], 0
	v_mfma_f32_16x16x32_bf16 v[6:9], v[30:33], v[6:9], 0
	s_waitcnt lgkmcnt(0)
	v_mfma_f32_16x16x32_bf16 v[62:65], v[14:17], v[22:25], v[10:13]
	s_nop 4
	ds_read_b128 v[10:13], v80 offset:62976
	v_mfma_f32_16x16x32_bf16 v[50:53], v[116:119], v[22:25], v[6:9]
	s_nop 2
	ds_read_b128 v[6:9], v79 offset:26112
	v_mfma_f32_16x16x32_bf16 v[38:41], v[2:5], v[34:37], 0
	v_mfma_f32_16x16x32_bf16 v[34:37], v[30:33], v[34:37], 0
	v_mfma_f32_16x16x32_bf16 v[2:5], v[2:5], v[46:49], 0
	v_mfma_f32_16x16x32_bf16 v[108:111], v[30:33], v[46:49], 0
	s_waitcnt lgkmcnt(0)
	v_mfma_f32_16x16x32_bf16 v[46:49], v[14:17], v[6:9], v[38:41]
	v_mfma_f32_16x16x32_bf16 v[42:45], v[10:13], v[6:9], v[42:45]
	v_mfma_f32_16x16x32_bf16 v[38:41], v[112:115], v[6:9], v[70:73]
	v_mfma_f32_16x16x32_bf16 v[34:37], v[116:119], v[6:9], v[34:37]
	ds_read_b128 v[6:9], v79 offset:27648
	s_nop 0
	v_add_u32_e32 v72, s0, v78
	v_ashrrev_i32_e32 v73, 31, v72
	s_waitcnt lgkmcnt(0)
	v_mfma_f32_16x16x32_bf16 v[30:33], v[14:17], v[6:9], v[84:87]
	v_or_b32_e32 v70, s1, v82
	s_nop 1
	ds_read_b128 v[84:87], v79 offset:29184
	v_lshlrev_b64 v[74:75], 10, v[72:73]
	v_mfma_f32_16x16x32_bf16 v[58:61], v[10:13], v[22:25], v[18:21]
	v_lshl_add_u64 v[74:75], s[22:23], 0, v[74:75]
	v_cmp_gt_i32_e32 vcc, s15, v70
	v_ashrrev_i32_e32 v71, 31, v70
	v_mfma_f32_16x16x32_bf16 v[54:57], v[112:115], v[22:25], v[26:29]
	s_waitcnt lgkmcnt(0)
	s_barrier
	v_mfma_f32_16x16x32_bf16 v[26:29], v[10:13], v[6:9], v[88:91]
	v_mfma_f32_16x16x32_bf16 v[22:25], v[112:115], v[6:9], v[92:95]
	v_mfma_f32_16x16x32_bf16 v[18:21], v[116:119], v[6:9], v[96:99]
	v_mfma_f32_16x16x32_bf16 v[14:17], v[14:17], v[84:87], v[2:5]
	v_mfma_f32_16x16x32_bf16 v[10:13], v[10:13], v[84:87], v[100:103]
	v_mfma_f32_16x16x32_bf16 v[6:9], v[112:115], v[84:87], v[104:107]
	v_mfma_f32_16x16x32_bf16 v[2:5], v[116:119], v[84:87], v[108:111]
	v_lshl_add_u64 v[252:253], v[70:71], 2, s[30:31]
	global_load_dwordx4 v[240:243], v[252:253], off
	global_load_dwordx4 v[244:247], v[252:253], off offset:16
	global_load_dwordx4 v[248:251], v[252:253], off offset:128
	global_load_dwordx4 v[252:255], v[252:253], off offset:144
	s_waitcnt vmcnt(0)
	s_and_saveexec_b64 s[0:1], vcc
	s_cbranch_execz .LBB0_1167
	v_add_f32_e32 v62, v62, v240
	v_add_f32_e32 v63, v63, v241
	v_add_f32_e32 v64, v64, v242
	v_add_f32_e32 v65, v65, v243
	v_add_f32_e32 v58, v58, v244
	v_add_f32_e32 v59, v59, v245
	v_add_f32_e32 v60, v60, v246
	v_add_f32_e32 v61, v61, v247
	v_mul_f32_e32 v62, 0xbfb8aa3b, v62
	v_mul_f32_e32 v63, 0xbfb8aa3b, v63
	v_mul_f32_e32 v64, 0xbfb8aa3b, v64
	v_mul_f32_e32 v65, 0xbfb8aa3b, v65
	v_mul_f32_e32 v58, 0xbfb8aa3b, v58
	v_mul_f32_e32 v59, 0xbfb8aa3b, v59
	v_mul_f32_e32 v60, 0xbfb8aa3b, v60
	v_mul_f32_e32 v61, 0xbfb8aa3b, v61
	v_exp_f32_e32 v62, v62
	v_exp_f32_e32 v63, v63
	v_exp_f32_e32 v64, v64
	v_exp_f32_e32 v65, v65
	v_exp_f32_e32 v58, v58
	v_exp_f32_e32 v59, v59
	v_exp_f32_e32 v60, v60
	v_exp_f32_e32 v61, v61
	v_add_f32_e32 v62, 1.0, v62
	v_add_f32_e32 v63, 1.0, v63
	v_add_f32_e32 v64, 1.0, v64
	v_add_f32_e32 v65, 1.0, v65
	v_add_f32_e32 v58, 1.0, v58
	v_add_f32_e32 v59, 1.0, v59
	v_add_f32_e32 v60, 1.0, v60
	v_add_f32_e32 v61, 1.0, v61
	v_rcp_f32_e32 v62, v62
	v_rcp_f32_e32 v63, v63
	v_rcp_f32_e32 v64, v64
	v_rcp_f32_e32 v65, v65
	v_rcp_f32_e32 v73, v58
	v_rcp_f32_e32 v83, v59
	v_rcp_f32_e32 v84, v60
	v_rcp_f32_e32 v61, v61
	v_cvt_pk_bf16_f32 v58, v62, v63
	v_cvt_pk_bf16_f32 v59, v64, v65
	v_cvt_pk_bf16_f32 v60, v73, v83
	v_cvt_pk_bf16_f32 v61, v84, v61
	v_lshl_add_u64 v[62:63], v[70:71], 1, v[74:75]
	global_store_dwordx4 v[62:63], v[58:61], off
; DI unsigned pack2(float a, float b) { f32x2_t v = {a, b}; bf16x2_t r = __builtin_convertvector(v, bf16x2_t); return __builtin_bit_cast(unsigned, r); }
; DI float sigmoidf_(float x) { return __builtin_amdgcn_rcpf(1.f + __builtin_amdgcn_exp2f(-1.4426950408889634f * x)); }
; template <class Epi>
; DI void gemm_small(const u16* __restrict__ A, int lda, const u16* __restrict__ Bt, int ldb, int N, int K, u16* __restrict__ O, int ldo, Epi epi,
;                    char* smem, int& rot) {
;     ...
; #pragma unroll
;     for (int mi = 0; mi < 4; ++mi) {
; #pragma unroll
;       for (int np = 0; np < 2; ++np) {
;         const int m = m0 + wm * 64 + mi * 16 + r16;
;         const int n = n0 + wn * 64 + np * 32 + quad * 8;
;         if (n < N) {
;           const f32x4 v0 = epi(n, acc[mi][2 * np]), v1 = epi(n + 4, acc[mi][2 * np + 1]);
;           uint4 o; o.x = pack2(v0[0], v0[1]); o.y = pack2(v0[2], v0[3]); o.z = pack2(v1[0], v1[1]); o.w = pack2(v1[2], v1[3]);
;           *(uint4*)(O + (size_t)m * ldo + n) = o;
;         }
;       }
;       __builtin_amdgcn_sched_barrier(0);
; __global__ void __launch_bounds__(512) fwd_megakernel(Params p) {
;     ...
;                      [=](int n, f32x4 v) {
;                        const float4 b = *(const float4*)(a0 + n);
;                        f32x4 o = {sigmoidf_(v[0] + b.x), sigmoidf_(v[1] + b.y), sigmoidf_(v[2] + b.z), sigmoidf_(v[3] + b.w)};
;                        return o;
.LBB0_1167:
	s_or_b64 exec, exec, s[0:1]
	s_nop 0
	v_or_b32_e32 v58, 32, v70
	v_cmp_gt_i32_e64 s[0:1], s15, v58
	s_and_saveexec_b64 s[38:39], s[0:1]
	s_cbranch_execz .LBB0_1169
	v_add_f32_e32 v54, v54, v248
	v_add_f32_e32 v55, v55, v249
	v_add_f32_e32 v56, v56, v250
	v_add_f32_e32 v57, v57, v251
	v_add_f32_e32 v50, v50, v252
	v_add_f32_e32 v51, v51, v253
	v_add_f32_e32 v52, v52, v254
	v_add_f32_e32 v53, v53, v255
	v_mul_f32_e32 v54, 0xbfb8aa3b, v54
	v_mul_f32_e32 v55, 0xbfb8aa3b, v55
	v_mul_f32_e32 v56, 0xbfb8aa3b, v56
	v_mul_f32_e32 v57, 0xbfb8aa3b, v57
	v_mul_f32_e32 v50, 0xbfb8aa3b, v50
	v_mul_f32_e32 v51, 0xbfb8aa3b, v51
	v_mul_f32_e32 v52, 0xbfb8aa3b, v52
	v_mul_f32_e32 v53, 0xbfb8aa3b, v53
	v_exp_f32_e32 v54, v54
	v_exp_f32_e32 v55, v55
	v_exp_f32_e32 v56, v56
	v_exp_f32_e32 v57, v57
	v_exp_f32_e32 v50, v50
	v_exp_f32_e32 v51, v51
	v_exp_f32_e32 v52, v52
	v_exp_f32_e32 v53, v53
	v_add_f32_e32 v54, 1.0, v54
	v_add_f32_e32 v55, 1.0, v55
	v_add_f32_e32 v56, 1.0, v56
	v_add_f32_e32 v57, 1.0, v57
	v_add_f32_e32 v50, 1.0, v50
	v_add_f32_e32 v51, 1.0, v51
	v_add_f32_e32 v52, 1.0, v52
	v_add_f32_e32 v53, 1.0, v53
	v_rcp_f32_e32 v54, v54
	v_rcp_f32_e32 v55, v55
	v_rcp_f32_e32 v56, v56
	v_rcp_f32_e32 v57, v57
	v_rcp_f32_e32 v58, v50
	v_rcp_f32_e32 v59, v51
	v_rcp_f32_e32 v60, v52
	v_rcp_f32_e32 v53, v53
	v_cvt_pk_bf16_f32 v50, v54, v55
	v_cvt_pk_bf16_f32 v51, v56, v57
	v_cvt_pk_bf16_f32 v52, v58, v59
	v_cvt_pk_bf16_f32 v53, v60, v53
	v_lshl_add_u64 v[54:55], v[70:71], 1, v[74:75]
	global_store_dwordx4 v[54:55], v[50:53], off offset:64
.LBB0_1169:
	s_or_b64 exec, exec, s[38:39]
	s_nop 0
	v_or_b32_e32 v50, 16, v72
	v_ashrrev_i32_e32 v51, 31, v50
	v_lshlrev_b64 v[50:51], 10, v[50:51]
	v_lshl_add_u64 v[50:51], s[22:23], 0, v[50:51]
	s_and_saveexec_b64 s[38:39], vcc
	s_cbranch_execz .LBB0_1171
	v_add_f32_e32 v46, v46, v240
	v_add_f32_e32 v47, v47, v241
	v_add_f32_e32 v48, v48, v242
	v_add_f32_e32 v49, v49, v243
	v_add_f32_e32 v42, v42, v244
	v_add_f32_e32 v43, v43, v245
	v_add_f32_e32 v44, v44, v246
	v_add_f32_e32 v45, v45, v247
	v_mul_f32_e32 v46, 0xbfb8aa3b, v46
	v_mul_f32_e32 v47, 0xbfb8aa3b, v47
	v_mul_f32_e32 v48, 0xbfb8aa3b, v48
	v_mul_f32_e32 v49, 0xbfb8aa3b, v49
	v_mul_f32_e32 v42, 0xbfb8aa3b, v42
	v_mul_f32_e32 v43, 0xbfb8aa3b, v43
	v_mul_f32_e32 v44, 0xbfb8aa3b, v44
	v_mul_f32_e32 v45, 0xbfb8aa3b, v45
	v_exp_f32_e32 v46, v46
	v_exp_f32_e32 v47, v47
	v_exp_f32_e32 v48, v48
	v_exp_f32_e32 v49, v49
	v_exp_f32_e32 v42, v42
	v_exp_f32_e32 v43, v43
	v_exp_f32_e32 v44, v44
	v_exp_f32_e32 v45, v45
	v_add_f32_e32 v46, 1.0, v46
	v_add_f32_e32 v47, 1.0, v47
	v_add_f32_e32 v48, 1.0, v48
	v_add_f32_e32 v49, 1.0, v49
	v_add_f32_e32 v42, 1.0, v42
	v_add_f32_e32 v43, 1.0, v43
	v_add_f32_e32 v44, 1.0, v44
	v_add_f32_e32 v45, 1.0, v45
	v_rcp_f32_e32 v46, v46
	v_rcp_f32_e32 v47, v47
	v_rcp_f32_e32 v48, v48
	v_rcp_f32_e32 v49, v49
	v_rcp_f32_e32 v52, v42
	v_rcp_f32_e32 v53, v43
	v_rcp_f32_e32 v54, v44
	v_rcp_f32_e32 v45, v45
	v_cvt_pk_bf16_f32 v42, v46, v47
	v_cvt_pk_bf16_f32 v43, v48, v49
	v_cvt_pk_bf16_f32 v44, v52, v53
	v_cvt_pk_bf16_f32 v45, v54, v45
	v_lshl_add_u64 v[46:47], v[70:71], 1, v[50:51]
	global_store_dwordx4 v[46:47], v[42:45], off
.LBB0_1171:
	s_or_b64 exec, exec, s[38:39]
	s_and_saveexec_b64 s[38:39], s[0:1]
	s_cbranch_execz .LBB0_1173
	v_add_f32_e32 v38, v38, v248
	v_add_f32_e32 v39, v39, v249
	v_add_f32_e32 v40, v40, v250
	v_add_f32_e32 v41, v41, v251
	v_add_f32_e32 v34, v34, v252
	v_add_f32_e32 v35, v35, v253
	v_add_f32_e32 v36, v36, v254
	v_add_f32_e32 v37, v37, v255
	v_mul_f32_e32 v38, 0xbfb8aa3b, v38
	v_mul_f32_e32 v39, 0xbfb8aa3b, v39
	v_mul_f32_e32 v40, 0xbfb8aa3b, v40
	v_mul_f32_e32 v41, 0xbfb8aa3b, v41
	v_mul_f32_e32 v34, 0xbfb8aa3b, v34
	v_mul_f32_e32 v35, 0xbfb8aa3b, v35
	v_mul_f32_e32 v36, 0xbfb8aa3b, v36
	v_mul_f32_e32 v37, 0xbfb8aa3b, v37
	v_exp_f32_e32 v38, v38
	v_exp_f32_e32 v39, v39
	v_exp_f32_e32 v40, v40
	v_exp_f32_e32 v41, v41
	v_exp_f32_e32 v34, v34
	v_exp_f32_e32 v35, v35
	v_exp_f32_e32 v36, v36
	v_exp_f32_e32 v37, v37
	v_add_f32_e32 v38, 1.0, v38
	v_add_f32_e32 v39, 1.0, v39
	v_add_f32_e32 v40, 1.0, v40
	v_add_f32_e32 v41, 1.0, v41
	v_add_f32_e32 v34, 1.0, v34
	v_add_f32_e32 v35, 1.0, v35
	v_add_f32_e32 v36, 1.0, v36
	v_add_f32_e32 v37, 1.0, v37
	v_rcp_f32_e32 v38, v38
	v_rcp_f32_e32 v39, v39
	v_rcp_f32_e32 v40, v40
	v_rcp_f32_e32 v41, v41
	v_rcp_f32_e32 v42, v34
	v_rcp_f32_e32 v43, v35
	v_rcp_f32_e32 v44, v36
	v_rcp_f32_e32 v37, v37
	v_cvt_pk_bf16_f32 v34, v38, v39
	v_cvt_pk_bf16_f32 v35, v40, v41
	v_cvt_pk_bf16_f32 v36, v42, v43
	v_cvt_pk_bf16_f32 v37, v44, v37
	v_lshl_add_u64 v[38:39], v[70:71], 1, v[50:51]
	global_store_dwordx4 v[38:39], v[34:37], off offset:64
; DI unsigned pack2(float a, float b) { f32x2_t v = {a, b}; bf16x2_t r = __builtin_convertvector(v, bf16x2_t); return __builtin_bit_cast(unsigned, r); }
; DI float sigmoidf_(float x) { return __builtin_amdgcn_rcpf(1.f + __builtin_amdgcn_exp2f(-1.4426950408889634f * x)); }
; template <class Epi>
; DI void gemm_small(const u16* __restrict__ A, int lda, const u16* __restrict__ Bt, int ldb, int N, int K, u16* __restrict__ O, int ldo, Epi epi,
;                    char* smem, int& rot) {
;     ...
; #pragma unroll
;     for (int mi = 0; mi < 4; ++mi) {
; #pragma unroll
;       for (int np = 0; np < 2; ++np) {
;         const int m = m0 + wm * 64 + mi * 16 + r16;
;         const int n = n0 + wn * 64 + np * 32 + quad * 8;
;         if (n < N) {
;           const f32x4 v0 = epi(n, acc[mi][2 * np]), v1 = epi(n + 4, acc[mi][2 * np + 1]);
;           uint4 o; o.x = pack2(v0[0], v0[1]); o.y = pack2(v0[2], v0[3]); o.z = pack2(v1[0], v1[1]); o.w = pack2(v1[2], v1[3]);
;           *(uint4*)(O + (size_t)m * ldo + n) = o;
;         }
;       }
;       __builtin_amdgcn_sched_barrier(0);
; __global__ void __launch_bounds__(512) fwd_megakernel(Params p) {
;     ...
;                      [=](int n, f32x4 v) {
;                        const float4 b = *(const float4*)(a0 + n);
;                        f32x4 o = {sigmoidf_(v[0] + b.x), sigmoidf_(v[1] + b.y), sigmoidf_(v[2] + b.z), sigmoidf_(v[3] + b.w)};
;                        return o;
.LBB0_1173:
	s_or_b64 exec, exec, s[38:39]
	s_nop 0
	v_or_b32_e32 v34, 32, v72
	v_ashrrev_i32_e32 v35, 31, v34
	v_lshlrev_b64 v[34:35], 10, v[34:35]
	v_lshl_add_u64 v[34:35], s[22:23], 0, v[34:35]
	s_and_saveexec_b64 s[38:39], vcc
	s_cbranch_execz .LBB0_1175
	v_add_f32_e32 v30, v30, v240
	v_add_f32_e32 v31, v31, v241
	v_add_f32_e32 v32, v32, v242
	v_add_f32_e32 v33, v33, v243
	v_add_f32_e32 v26, v26, v244
	v_add_f32_e32 v27, v27, v245
	v_add_f32_e32 v28, v28, v246
	v_add_f32_e32 v29, v29, v247
	v_mul_f32_e32 v30, 0xbfb8aa3b, v30
	v_mul_f32_e32 v31, 0xbfb8aa3b, v31
	v_mul_f32_e32 v32, 0xbfb8aa3b, v32
	v_mul_f32_e32 v33, 0xbfb8aa3b, v33
	v_mul_f32_e32 v26, 0xbfb8aa3b, v26
	v_mul_f32_e32 v27, 0xbfb8aa3b, v27
	v_mul_f32_e32 v28, 0xbfb8aa3b, v28
	v_mul_f32_e32 v29, 0xbfb8aa3b, v29
	v_exp_f32_e32 v30, v30
	v_exp_f32_e32 v31, v31
	v_exp_f32_e32 v32, v32
	v_exp_f32_e32 v33, v33
	v_exp_f32_e32 v26, v26
	v_exp_f32_e32 v27, v27
	v_exp_f32_e32 v28, v28
	v_exp_f32_e32 v29, v29
	v_add_f32_e32 v30, 1.0, v30
	v_add_f32_e32 v31, 1.0, v31
	v_add_f32_e32 v32, 1.0, v32
	v_add_f32_e32 v33, 1.0, v33
	v_add_f32_e32 v26, 1.0, v26
	v_add_f32_e32 v27, 1.0, v27
	v_add_f32_e32 v28, 1.0, v28
	v_add_f32_e32 v29, 1.0, v29
	v_rcp_f32_e32 v30, v30
	v_rcp_f32_e32 v31, v31
	v_rcp_f32_e32 v32, v32
	v_rcp_f32_e32 v33, v33
	v_rcp_f32_e32 v36, v26
	v_rcp_f32_e32 v37, v27
	v_rcp_f32_e32 v38, v28
	v_rcp_f32_e32 v29, v29
	v_cvt_pk_bf16_f32 v26, v30, v31
	v_cvt_pk_bf16_f32 v27, v32, v33
	v_cvt_pk_bf16_f32 v28, v36, v37
	v_cvt_pk_bf16_f32 v29, v38, v29
	v_lshl_add_u64 v[30:31], v[70:71], 1, v[34:35]
	global_store_dwordx4 v[30:31], v[26:29], off
.LBB0_1175:
	s_or_b64 exec, exec, s[38:39]
	s_and_saveexec_b64 s[38:39], s[0:1]
	s_cbranch_execz .LBB0_1177
	v_add_f32_e32 v22, v22, v248
	v_add_f32_e32 v23, v23, v249
	v_add_f32_e32 v24, v24, v250
	v_add_f32_e32 v25, v25, v251
	v_add_f32_e32 v18, v18, v252
	v_add_f32_e32 v19, v19, v253
	v_add_f32_e32 v20, v20, v254
	v_add_f32_e32 v21, v21, v255
	v_mul_f32_e32 v22, 0xbfb8aa3b, v22
	v_mul_f32_e32 v23, 0xbfb8aa3b, v23
	v_mul_f32_e32 v24, 0xbfb8aa3b, v24
	v_mul_f32_e32 v25, 0xbfb8aa3b, v25
	v_mul_f32_e32 v18, 0xbfb8aa3b, v18
	v_mul_f32_e32 v19, 0xbfb8aa3b, v19
	v_mul_f32_e32 v20, 0xbfb8aa3b, v20
	v_mul_f32_e32 v21, 0xbfb8aa3b, v21
	v_exp_f32_e32 v22, v22
	v_exp_f32_e32 v23, v23
	v_exp_f32_e32 v24, v24
	v_exp_f32_e32 v25, v25
	v_exp_f32_e32 v18, v18
	v_exp_f32_e32 v19, v19
	v_exp_f32_e32 v20, v20
	v_exp_f32_e32 v21, v21
	v_add_f32_e32 v22, 1.0, v22
	v_add_f32_e32 v23, 1.0, v23
	v_add_f32_e32 v24, 1.0, v24
	v_add_f32_e32 v25, 1.0, v25
	v_add_f32_e32 v18, 1.0, v18
	v_add_f32_e32 v19, 1.0, v19
	v_add_f32_e32 v20, 1.0, v20
	v_add_f32_e32 v21, 1.0, v21
	v_rcp_f32_e32 v22, v22
	v_rcp_f32_e32 v23, v23
	v_rcp_f32_e32 v24, v24
	v_rcp_f32_e32 v25, v25
	v_rcp_f32_e32 v26, v18
	v_rcp_f32_e32 v27, v19
	v_rcp_f32_e32 v28, v20
	v_rcp_f32_e32 v21, v21
	v_cvt_pk_bf16_f32 v18, v22, v23
	v_cvt_pk_bf16_f32 v19, v24, v25
	v_cvt_pk_bf16_f32 v20, v26, v27
	v_cvt_pk_bf16_f32 v21, v28, v21
	v_lshl_add_u64 v[22:23], v[70:71], 1, v[34:35]
	global_store_dwordx4 v[22:23], v[18:21], off offset:64
.LBB0_1177:
	s_or_b64 exec, exec, s[38:39]
	s_nop 0
	v_or_b32_e32 v18, 48, v72
	v_ashrrev_i32_e32 v19, 31, v18
	v_lshlrev_b64 v[18:19], 10, v[18:19]
	v_lshl_add_u64 v[18:19], s[22:23], 0, v[18:19]
	s_and_saveexec_b64 s[38:39], vcc
	s_cbranch_execz .LBB0_1179
	v_add_f32_e32 v14, v14, v240
	v_add_f32_e32 v15, v15, v241
	v_add_f32_e32 v16, v16, v242
	v_add_f32_e32 v17, v17, v243
	v_add_f32_e32 v10, v10, v244
	v_add_f32_e32 v11, v11, v245
	v_add_f32_e32 v12, v12, v246
	v_add_f32_e32 v13, v13, v247
	v_mul_f32_e32 v14, 0xbfb8aa3b, v14
	v_mul_f32_e32 v15, 0xbfb8aa3b, v15
	v_mul_f32_e32 v16, 0xbfb8aa3b, v16
	v_mul_f32_e32 v17, 0xbfb8aa3b, v17
	v_mul_f32_e32 v10, 0xbfb8aa3b, v10
	v_mul_f32_e32 v11, 0xbfb8aa3b, v11
	v_mul_f32_e32 v12, 0xbfb8aa3b, v12
	v_mul_f32_e32 v13, 0xbfb8aa3b, v13
	v_exp_f32_e32 v14, v14
	v_exp_f32_e32 v15, v15
	v_exp_f32_e32 v16, v16
	v_exp_f32_e32 v17, v17
	v_exp_f32_e32 v10, v10
	v_exp_f32_e32 v11, v11
	v_exp_f32_e32 v12, v12
	v_exp_f32_e32 v13, v13
	v_add_f32_e32 v14, 1.0, v14
	v_add_f32_e32 v15, 1.0, v15
	v_add_f32_e32 v16, 1.0, v16
	v_add_f32_e32 v17, 1.0, v17
	v_add_f32_e32 v10, 1.0, v10
	v_add_f32_e32 v11, 1.0, v11
	v_add_f32_e32 v12, 1.0, v12
	v_add_f32_e32 v13, 1.0, v13
	v_rcp_f32_e32 v14, v14
	v_rcp_f32_e32 v15, v15
	v_rcp_f32_e32 v16, v16
	v_rcp_f32_e32 v17, v17
	v_rcp_f32_e32 v20, v10
	v_rcp_f32_e32 v21, v11
	v_rcp_f32_e32 v22, v12
	v_rcp_f32_e32 v13, v13
	v_cvt_pk_bf16_f32 v10, v14, v15
	v_cvt_pk_bf16_f32 v11, v16, v17
	v_cvt_pk_bf16_f32 v12, v20, v21
	v_cvt_pk_bf16_f32 v13, v22, v13
	v_lshl_add_u64 v[14:15], v[70:71], 1, v[18:19]
	global_store_dwordx4 v[14:15], v[10:13], off
.LBB0_1179:
	s_or_b64 exec, exec, s[38:39]
	s_and_saveexec_b64 s[38:39], s[0:1]
	s_cbranch_execz .LBB0_1164
	v_add_f32_e32 v6, v6, v248
	v_add_f32_e32 v7, v7, v249
	v_add_f32_e32 v8, v8, v250
	v_add_f32_e32 v9, v9, v251
	v_add_f32_e32 v2, v2, v252
	v_add_f32_e32 v3, v3, v253
	v_add_f32_e32 v4, v4, v254
	v_add_f32_e32 v5, v5, v255
	v_mul_f32_e32 v6, 0xbfb8aa3b, v6
	v_mul_f32_e32 v7, 0xbfb8aa3b, v7
	v_mul_f32_e32 v8, 0xbfb8aa3b, v8
	v_mul_f32_e32 v9, 0xbfb8aa3b, v9
	v_mul_f32_e32 v2, 0xbfb8aa3b, v2
	v_mul_f32_e32 v3, 0xbfb8aa3b, v3
	v_mul_f32_e32 v4, 0xbfb8aa3b, v4
	v_mul_f32_e32 v5, 0xbfb8aa3b, v5
	v_exp_f32_e32 v6, v6
	v_exp_f32_e32 v7, v7
	v_exp_f32_e32 v8, v8
	v_exp_f32_e32 v9, v9
	v_exp_f32_e32 v2, v2
	v_exp_f32_e32 v3, v3
	v_exp_f32_e32 v4, v4
	v_exp_f32_e32 v5, v5
	v_add_f32_e32 v6, 1.0, v6
	v_add_f32_e32 v7, 1.0, v7
	v_add_f32_e32 v8, 1.0, v8
	v_add_f32_e32 v9, 1.0, v9
	v_add_f32_e32 v2, 1.0, v2
	v_add_f32_e32 v3, 1.0, v3
	v_add_f32_e32 v4, 1.0, v4
	v_add_f32_e32 v5, 1.0, v5
	v_rcp_f32_e32 v6, v6
	v_rcp_f32_e32 v7, v7
	v_rcp_f32_e32 v8, v8
	v_rcp_f32_e32 v9, v9
	v_rcp_f32_e32 v10, v2
	v_rcp_f32_e32 v11, v3
	v_rcp_f32_e32 v12, v4
	v_rcp_f32_e32 v5, v5
	v_cvt_pk_bf16_f32 v2, v6, v7
	v_cvt_pk_bf16_f32 v3, v8, v9
	v_cvt_pk_bf16_f32 v4, v10, v11
	v_cvt_pk_bf16_f32 v5, v12, v5
	v_lshl_add_u64 v[6:7], v[70:71], 1, v[18:19]
	global_store_dwordx4 v[6:7], v[2:5], off offset:64
	s_branch .LBB0_1164

; template <class Epi>
; DI void gemm_small(const u16* __restrict__ A, int lda, const u16* __restrict__ Bt, int ldb, int N, int K, u16* __restrict__ O, int ldo, Epi epi,
;                    char* smem, int& rot) {
;     ...
;   for (int tile = first; tile < ntiles; tile += gridDim.x) {
;     const int grp = tile / (8 * NT), rem = tile - grp * 8 * NT;
;     const int mt = grp * 8 + (rem & 7), nt = rem >> 3;
;     const int m0 = mt << 8, n0 = nt << 7;
;     const u16* Ap = A + (size_t)(m0 + ldrow) * lda + ldkc * 8;
;     const u16* Bp = Bt + (size_t)(n0 + (ldrow & ~31) + pg8::perm32(ldrow & 31)) * ldb + ldkc * 8;
;     uint4 ra0 = *(const uint4*)Ap, ra1 = *(const uint4*)(Ap + (size_t)128 * lda);
;     uint4 rb0 = *(const uint4*)Bp;
;     f32x4 acc[4][4];
; #pragma unroll
;     for (int i = 0; i < 4; ++i)
; #pragma unroll
;       for (int j = 0; j < 4; ++j) acc[i][j] = (f32x4){0.f, 0.f, 0.f, 0.f};
;     *(uint4*)(sA + ldrow * 48 + ldkc * 8) = ra0;
;     *(uint4*)(sA + (ldrow + 128) * 48 + ldkc * 8) = ra1;
;     *(uint4*)(sB + ldrow * 48 + ldkc * 8) = rb0;
;     __syncthreads();
;     for (int kt = 0; kt < KT; ++kt) {
;       const int cur = kt & 1;
;       if (kt + 1 < KT) {
;         const int ko = (kt + 1) << 5;
;         ra0 = *(const uint4*)(Ap + ko); ra1 = *(const uint4*)(Ap + (size_t)128 * lda + ko);
;         rb0 = *(const uint4*)(Bp + ko);
;       }
;       const u16* as = sA + cur * 256 * 48 + (wm * 64 + r16) * 48 + quad * 8;
;       const u16* bs = sB + cur * 128 * 48 + (wn * 64 + r16) * 48 + quad * 8;
;       bf16x8 af[4], bfr[4];
; #pragma unroll
;       for (int i = 0; i < 4; ++i) { af[i] = *(const bf16x8*)(as + i * 16 * 48); bfr[i] = *(const bf16x8*)(bs + i * 16 * 48); }
; #pragma unroll
;       for (int mi = 0; mi < 4; ++mi)
; #pragma unroll
;         for (int ni = 0; ni < 4; ++ni) acc[mi][ni] = MFMA16(bfr[ni], af[mi], acc[mi][ni]);
;       if (kt + 1 < KT) {
;         u16* a2 = sA + (cur ^ 1) * 256 * 48; u16* b2 = sB + (cur ^ 1) * 128 * 48;
;         *(uint4*)(a2 + ldrow * 48 + ldkc * 8) = ra0;
;         *(uint4*)(a2 + (ldrow + 128) * 48 + ldkc * 8) = ra1;
;         *(uint4*)(b2 + ldrow * 48 + ldkc * 8) = rb0;
;       }
;       __syncthreads();
;     }
; #pragma unroll
;     for (int mi = 0; mi < 4; ++mi) {
; #pragma unroll
;       for (int np = 0; np < 2; ++np) {
;         const int m = m0 + wm * 64 + mi * 16 + r16;
.LBB0_1187:
	s_ashr_i32 s0, s26, 31
	s_lshr_b32 s0, s0, 27
	s_add_i32 s0, s26, s0
	s_ashr_i32 s1, s0, 5
	s_lshl_b32 s0, s1, 11
	s_and_b32 s34, s33, 0x700
	s_lshl_b32 s1, s1, 9
	s_or_b32 s0, s0, s34
	s_sub_i32 s1, s28, s1
	s_and_b32 s1, s1, 0xffffff80
	v_add_u32_e32 v2, s0, v1
	v_mad_i64_i32 v[50:51], s[36:37], v2, s9, v[66:67]
	v_add_u32_e32 v2, s1, v76
	v_ashrrev_i32_e32 v3, 31, v2
	v_add_co_u32_e32 v54, vcc, s18, v50
	v_lshlrev_b64 v[2:3], 7, v[2:3]
	s_nop 0
	v_addc_co_u32_e32 v55, vcc, 0, v51, vcc
	v_lshl_add_u64 v[58:59], v[68:69], 0, v[2:3]
	global_load_dwordx4 v[2:5], v[50:51], off
	global_load_dwordx4 v[6:9], v[54:55], off
	global_load_dwordx4 v[10:13], v[58:59], off
	s_waitcnt vmcnt(2)
	ds_write_b128 v77, v[2:5]
	s_waitcnt vmcnt(1)
	ds_write_b128 v77, v[6:9] offset:12288
	s_waitcnt vmcnt(0)
	ds_write_b128 v77, v[10:13] offset:49152
	s_waitcnt lgkmcnt(0)
	s_barrier
	ds_read_b128 v[2:5], v80 offset:49152
	ds_read_b128 v[6:9], v79
	ds_read_b128 v[14:17], v80 offset:50688
	ds_read_b128 v[22:25], v80 offset:52224
	ds_read_b128 v[30:33], v80 offset:53760
	ds_read_b128 v[34:37], v79 offset:1536
	ds_read_b128 v[46:49], v79 offset:3072
	s_waitcnt lgkmcnt(0)
	v_mfma_f32_16x16x32_bf16 v[84:87], v[2:5], v[46:49], 0
	v_mfma_f32_16x16x32_bf16 v[88:91], v[14:17], v[46:49], 0
	v_mfma_f32_16x16x32_bf16 v[92:95], v[22:25], v[46:49], 0
	v_mfma_f32_16x16x32_bf16 v[96:99], v[30:33], v[46:49], 0
	ds_read_b128 v[46:49], v79 offset:4608
	global_load_dwordx4 v[50:53], v[50:51], off offset:64
	s_nop 0
	global_load_dwordx4 v[54:57], v[54:55], off offset:64
	v_mfma_f32_16x16x32_bf16 v[18:21], v[14:17], v[6:9], 0
	v_mfma_f32_16x16x32_bf16 v[42:45], v[14:17], v[34:37], 0
	s_waitcnt lgkmcnt(0)
	v_mfma_f32_16x16x32_bf16 v[100:103], v[14:17], v[46:49], 0
	global_load_dwordx4 v[14:17], v[58:59], off offset:64
	s_waitcnt vmcnt(2)
	ds_write_b128 v77, v[50:53] offset:24576
	s_waitcnt vmcnt(1)
	ds_write_b128 v77, v[54:57] offset:36864
	s_waitcnt vmcnt(0)
	ds_write_b128 v77, v[14:17] offset:61440
	s_waitcnt lgkmcnt(0)
	s_barrier
	ds_read_b128 v[14:17], v80 offset:61440
	v_mfma_f32_16x16x32_bf16 v[26:29], v[22:25], v[6:9], 0
	ds_read_b128 v[112:115], v80 offset:64512
	ds_read_b128 v[116:119], v81 offset:16896
	v_mfma_f32_16x16x32_bf16 v[70:73], v[22:25], v[34:37], 0
	v_mfma_f32_16x16x32_bf16 v[104:107], v[22:25], v[46:49], 0
	ds_read_b128 v[22:25], v79 offset:24576
	v_mfma_f32_16x16x32_bf16 v[10:13], v[2:5], v[6:9], 0
	v_mfma_f32_16x16x32_bf16 v[6:9], v[30:33], v[6:9], 0
	s_waitcnt lgkmcnt(0)
	v_mfma_f32_16x16x32_bf16 v[62:65], v[14:17], v[22:25], v[10:13]
	s_nop 4
	ds_read_b128 v[10:13], v80 offset:62976
	v_mfma_f32_16x16x32_bf16 v[50:53], v[116:119], v[22:25], v[6:9]
	s_nop 2
	ds_read_b128 v[6:9], v79 offset:26112
	v_mfma_f32_16x16x32_bf16 v[38:41], v[2:5], v[34:37], 0
	v_mfma_f32_16x16x32_bf16 v[34:37], v[30:33], v[34:37], 0
	v_mfma_f32_16x16x32_bf16 v[2:5], v[2:5], v[46:49], 0
	v_mfma_f32_16x16x32_bf16 v[108:111], v[30:33], v[46:49], 0
	s_waitcnt lgkmcnt(0)
	v_mfma_f32_16x16x32_bf16 v[46:49], v[14:17], v[6:9], v[38:41]
	v_mfma_f32_16x16x32_bf16 v[42:45], v[10:13], v[6:9], v[42:45]
	v_mfma_f32_16x16x32_bf16 v[38:41], v[112:115], v[6:9], v[70:73]
	v_mfma_f32_16x16x32_bf16 v[34:37], v[116:119], v[6:9], v[34:37]
	ds_read_b128 v[6:9], v79 offset:27648
	s_nop 0
	v_add_u32_e32 v72, s0, v78
	v_ashrrev_i32_e32 v73, 31, v72
	s_waitcnt lgkmcnt(0)
	v_mfma_f32_16x16x32_bf16 v[30:33], v[14:17], v[6:9], v[84:87]
	v_or_b32_e32 v70, s1, v82
	s_nop 1
	ds_read_b128 v[84:87], v79 offset:29184
	v_lshlrev_b64 v[74:75], 10, v[72:73]
	v_mfma_f32_16x16x32_bf16 v[58:61], v[10:13], v[22:25], v[18:21]
	v_lshl_add_u64 v[74:75], s[22:23], 0, v[74:75]
	v_cmp_gt_i32_e32 vcc, s15, v70
	v_ashrrev_i32_e32 v71, 31, v70
	v_mfma_f32_16x16x32_bf16 v[54:57], v[112:115], v[22:25], v[26:29]
	s_waitcnt lgkmcnt(0)
	s_barrier
	v_mfma_f32_16x16x32_bf16 v[26:29], v[10:13], v[6:9], v[88:91]
	v_mfma_f32_16x16x32_bf16 v[22:25], v[112:115], v[6:9], v[92:95]
	v_mfma_f32_16x16x32_bf16 v[18:21], v[116:119], v[6:9], v[96:99]
	v_mfma_f32_16x16x32_bf16 v[14:17], v[14:17], v[84:87], v[2:5]
	v_mfma_f32_16x16x32_bf16 v[10:13], v[10:13], v[84:87], v[100:103]
	v_mfma_f32_16x16x32_bf16 v[6:9], v[112:115], v[84:87], v[104:107]
	v_mfma_f32_16x16x32_bf16 v[2:5], v[116:119], v[84:87], v[108:111]
	v_lshl_add_u64 v[252:253], v[70:71], 2, s[30:31]
	global_load_dwordx4 v[240:243], v[252:253], off
	global_load_dwordx4 v[244:247], v[252:253], off offset:16
	global_load_dwordx4 v[248:251], v[252:253], off offset:128
	global_load_dwordx4 v[252:255], v[252:253], off offset:144
	s_waitcnt vmcnt(0)
	s_and_saveexec_b64 s[0:1], vcc
	s_cbranch_execz .LBB0_1189
	v_add_f32_e32 v62, v62, v240
	v_add_f32_e32 v63, v63, v241
	v_add_f32_e32 v64, v64, v242
	v_add_f32_e32 v65, v65, v243
	v_add_f32_e32 v58, v58, v244
	v_add_f32_e32 v59, v59, v245
	v_add_f32_e32 v60, v60, v246
	v_add_f32_e32 v61, v61, v247
	v_mul_f32_e32 v62, 0xbfb8aa3b, v62
	v_mul_f32_e32 v63, 0xbfb8aa3b, v63
	v_mul_f32_e32 v64, 0xbfb8aa3b, v64
	v_mul_f32_e32 v65, 0xbfb8aa3b, v65
	v_mul_f32_e32 v58, 0xbfb8aa3b, v58
	v_mul_f32_e32 v59, 0xbfb8aa3b, v59
	v_mul_f32_e32 v60, 0xbfb8aa3b, v60
	v_mul_f32_e32 v61, 0xbfb8aa3b, v61
	v_exp_f32_e32 v62, v62
	v_exp_f32_e32 v63, v63
	v_exp_f32_e32 v64, v64
	v_exp_f32_e32 v65, v65
	v_exp_f32_e32 v58, v58
	v_exp_f32_e32 v59, v59
	v_exp_f32_e32 v60, v60
	v_exp_f32_e32 v61, v61
	v_add_f32_e32 v62, 1.0, v62
	v_add_f32_e32 v63, 1.0, v63
	v_add_f32_e32 v64, 1.0, v64
	v_add_f32_e32 v65, 1.0, v65
	v_add_f32_e32 v73, 1.0, v58
	v_add_f32_e32 v83, 1.0, v59
	v_add_f32_e32 v84, 1.0, v60
	v_add_f32_e32 v85, 1.0, v61
	v_rcp_f32_e32 v58, v62
	v_rcp_f32_e32 v59, v63
	v_rcp_f32_e32 v60, v64
	v_rcp_f32_e32 v61, v65
	v_rcp_f32_e32 v62, v73
	v_rcp_f32_e32 v63, v83
	v_rcp_f32_e32 v64, v84
	v_rcp_f32_e32 v65, v85
	v_pk_mul_f32 v[58:59], v[58:59], s[12:13] op_sel_hi:[1,0]
	v_pk_mul_f32 v[60:61], v[60:61], s[12:13] op_sel_hi:[1,0]
	v_pk_mul_f32 v[62:63], v[62:63], s[12:13] op_sel_hi:[1,0]
	v_pk_mul_f32 v[64:65], v[64:65], s[12:13] op_sel_hi:[1,0]
	v_cvt_pk_bf16_f32 v58, v58, v59
	v_cvt_pk_bf16_f32 v59, v60, v61
	v_cvt_pk_bf16_f32 v60, v62, v63
	v_cvt_pk_bf16_f32 v61, v64, v65
	v_lshl_add_u64 v[62:63], v[70:71], 1, v[74:75]
	global_store_dwordx4 v[62:63], v[58:61], off
; DI unsigned pack2(float a, float b) { f32x2_t v = {a, b}; bf16x2_t r = __builtin_convertvector(v, bf16x2_t); return __builtin_bit_cast(unsigned, r); }
; DI float sigmoidf_(float x) { return __builtin_amdgcn_rcpf(1.f + __builtin_amdgcn_exp2f(-1.4426950408889634f * x)); }
; template <class Epi>
; DI void gemm_small(const u16* __restrict__ A, int lda, const u16* __restrict__ Bt, int ldb, int N, int K, u16* __restrict__ O, int ldo, Epi epi,
;                    char* smem, int& rot) {
;     ...
; #pragma unroll
;     for (int mi = 0; mi < 4; ++mi) {
; #pragma unroll
;       for (int np = 0; np < 2; ++np) {
;         const int m = m0 + wm * 64 + mi * 16 + r16;
;         const int n = n0 + wn * 64 + np * 32 + quad * 8;
;         if (n < N) {
;           const f32x4 v0 = epi(n, acc[mi][2 * np]), v1 = epi(n + 4, acc[mi][2 * np + 1]);
;           uint4 o; o.x = pack2(v0[0], v0[1]); o.y = pack2(v0[2], v0[3]); o.z = pack2(v1[0], v1[1]); o.w = pack2(v1[2], v1[3]);
;           *(uint4*)(O + (size_t)m * ldo + n) = o;
;         }
;       }
;       __builtin_amdgcn_sched_barrier(0);
; __global__ void __launch_bounds__(512) fwd_megakernel(Params p) {
;     ...
;                      [=](int n, f32x4 v) {
;                        const float4 b = *(const float4*)(w0 + n);
;                        const float ce = 0.6065306597126334f;
;                        f32x4 o = {ce * sigmoidf_(v[0] + b.x), ce * sigmoidf_(v[1] + b.y), ce * sigmoidf_(v[2] + b.z), ce * sigmoidf_(v[3] + b.w)};
;                        return o;
.LBB0_1189:
	s_or_b64 exec, exec, s[0:1]
	s_nop 0
	v_or_b32_e32 v58, 32, v70
	v_cmp_gt_i32_e64 s[0:1], s15, v58
	s_and_saveexec_b64 s[36:37], s[0:1]
	s_cbranch_execz .LBB0_1191
	v_add_f32_e32 v54, v54, v248
	v_add_f32_e32 v55, v55, v249
	v_add_f32_e32 v56, v56, v250
	v_add_f32_e32 v57, v57, v251
	v_add_f32_e32 v50, v50, v252
	v_add_f32_e32 v51, v51, v253
	v_add_f32_e32 v52, v52, v254
	v_add_f32_e32 v53, v53, v255
	v_mul_f32_e32 v54, 0xbfb8aa3b, v54
	v_mul_f32_e32 v55, 0xbfb8aa3b, v55
	v_mul_f32_e32 v56, 0xbfb8aa3b, v56
	v_mul_f32_e32 v57, 0xbfb8aa3b, v57
	v_mul_f32_e32 v50, 0xbfb8aa3b, v50
	v_mul_f32_e32 v51, 0xbfb8aa3b, v51
	v_mul_f32_e32 v52, 0xbfb8aa3b, v52
	v_mul_f32_e32 v53, 0xbfb8aa3b, v53
	v_exp_f32_e32 v54, v54
	v_exp_f32_e32 v55, v55
	v_exp_f32_e32 v56, v56
	v_exp_f32_e32 v57, v57
	v_exp_f32_e32 v50, v50
	v_exp_f32_e32 v51, v51
	v_exp_f32_e32 v52, v52
	v_exp_f32_e32 v53, v53
	v_add_f32_e32 v54, 1.0, v54
	v_add_f32_e32 v55, 1.0, v55
	v_add_f32_e32 v56, 1.0, v56
	v_add_f32_e32 v57, 1.0, v57
	v_add_f32_e32 v58, 1.0, v50
	v_add_f32_e32 v59, 1.0, v51
	v_add_f32_e32 v60, 1.0, v52
	v_add_f32_e32 v61, 1.0, v53
	v_rcp_f32_e32 v50, v54
	v_rcp_f32_e32 v51, v55
	v_rcp_f32_e32 v52, v56
	v_rcp_f32_e32 v53, v57
	v_rcp_f32_e32 v54, v58
	v_rcp_f32_e32 v55, v59
	v_rcp_f32_e32 v56, v60
	v_rcp_f32_e32 v57, v61
	v_pk_mul_f32 v[50:51], v[50:51], s[12:13] op_sel_hi:[1,0]
	v_pk_mul_f32 v[52:53], v[52:53], s[12:13] op_sel_hi:[1,0]
	v_pk_mul_f32 v[54:55], v[54:55], s[12:13] op_sel_hi:[1,0]
	v_pk_mul_f32 v[56:57], v[56:57], s[12:13] op_sel_hi:[1,0]
	v_cvt_pk_bf16_f32 v50, v50, v51
	v_cvt_pk_bf16_f32 v51, v52, v53
	v_cvt_pk_bf16_f32 v52, v54, v55
	v_cvt_pk_bf16_f32 v53, v56, v57
	v_lshl_add_u64 v[54:55], v[70:71], 1, v[74:75]
	global_store_dwordx4 v[54:55], v[50:53], off offset:64
.LBB0_1191:
	s_or_b64 exec, exec, s[36:37]
	s_nop 0
	v_or_b32_e32 v50, 16, v72
	v_ashrrev_i32_e32 v51, 31, v50
	v_lshlrev_b64 v[50:51], 10, v[50:51]
	v_lshl_add_u64 v[50:51], s[22:23], 0, v[50:51]
	s_and_saveexec_b64 s[36:37], vcc
	s_cbranch_execz .LBB0_1193
	v_add_f32_e32 v46, v46, v240
	v_add_f32_e32 v47, v47, v241
	v_add_f32_e32 v48, v48, v242
	v_add_f32_e32 v49, v49, v243
	v_add_f32_e32 v42, v42, v244
	v_add_f32_e32 v43, v43, v245
	v_add_f32_e32 v44, v44, v246
	v_add_f32_e32 v45, v45, v247
	v_mul_f32_e32 v46, 0xbfb8aa3b, v46
	v_mul_f32_e32 v47, 0xbfb8aa3b, v47
	v_mul_f32_e32 v48, 0xbfb8aa3b, v48
	v_mul_f32_e32 v49, 0xbfb8aa3b, v49
	v_mul_f32_e32 v42, 0xbfb8aa3b, v42
	v_mul_f32_e32 v43, 0xbfb8aa3b, v43
	v_mul_f32_e32 v44, 0xbfb8aa3b, v44
	v_mul_f32_e32 v45, 0xbfb8aa3b, v45
	v_exp_f32_e32 v46, v46
	v_exp_f32_e32 v47, v47
	v_exp_f32_e32 v48, v48
	v_exp_f32_e32 v49, v49
	v_exp_f32_e32 v42, v42
	v_exp_f32_e32 v43, v43
	v_exp_f32_e32 v44, v44
	v_exp_f32_e32 v45, v45
	v_add_f32_e32 v46, 1.0, v46
	v_add_f32_e32 v47, 1.0, v47
	v_add_f32_e32 v48, 1.0, v48
	v_add_f32_e32 v49, 1.0, v49
	v_add_f32_e32 v52, 1.0, v42
	v_add_f32_e32 v53, 1.0, v43
	v_add_f32_e32 v54, 1.0, v44
	v_add_f32_e32 v55, 1.0, v45
	v_rcp_f32_e32 v42, v46
	v_rcp_f32_e32 v43, v47
	v_rcp_f32_e32 v44, v48
	v_rcp_f32_e32 v45, v49
	v_rcp_f32_e32 v46, v52
	v_rcp_f32_e32 v47, v53
	v_rcp_f32_e32 v48, v54
	v_rcp_f32_e32 v49, v55
	v_pk_mul_f32 v[42:43], v[42:43], s[12:13] op_sel_hi:[1,0]
	v_pk_mul_f32 v[44:45], v[44:45], s[12:13] op_sel_hi:[1,0]
	v_pk_mul_f32 v[46:47], v[46:47], s[12:13] op_sel_hi:[1,0]
	v_pk_mul_f32 v[48:49], v[48:49], s[12:13] op_sel_hi:[1,0]
	v_cvt_pk_bf16_f32 v42, v42, v43
	v_cvt_pk_bf16_f32 v43, v44, v45
	v_cvt_pk_bf16_f32 v44, v46, v47
	v_cvt_pk_bf16_f32 v45, v48, v49
	v_lshl_add_u64 v[46:47], v[70:71], 1, v[50:51]
	global_store_dwordx4 v[46:47], v[42:45], off
.LBB0_1193:
	s_or_b64 exec, exec, s[36:37]
	s_and_saveexec_b64 s[36:37], s[0:1]
	s_cbranch_execz .LBB0_1195
	v_add_f32_e32 v38, v38, v248
	v_add_f32_e32 v39, v39, v249
	v_add_f32_e32 v40, v40, v250
	v_add_f32_e32 v41, v41, v251
	v_add_f32_e32 v34, v34, v252
	v_add_f32_e32 v35, v35, v253
	v_add_f32_e32 v36, v36, v254
	v_add_f32_e32 v37, v37, v255
	v_mul_f32_e32 v38, 0xbfb8aa3b, v38
	v_mul_f32_e32 v39, 0xbfb8aa3b, v39
	v_mul_f32_e32 v40, 0xbfb8aa3b, v40
	v_mul_f32_e32 v41, 0xbfb8aa3b, v41
	v_mul_f32_e32 v34, 0xbfb8aa3b, v34
	v_mul_f32_e32 v35, 0xbfb8aa3b, v35
	v_mul_f32_e32 v36, 0xbfb8aa3b, v36
	v_mul_f32_e32 v37, 0xbfb8aa3b, v37
	v_exp_f32_e32 v38, v38
	v_exp_f32_e32 v39, v39
	v_exp_f32_e32 v40, v40
	v_exp_f32_e32 v41, v41
	v_exp_f32_e32 v34, v34
	v_exp_f32_e32 v35, v35
	v_exp_f32_e32 v36, v36
	v_exp_f32_e32 v37, v37
	v_add_f32_e32 v38, 1.0, v38
	v_add_f32_e32 v39, 1.0, v39
	v_add_f32_e32 v40, 1.0, v40
	v_add_f32_e32 v41, 1.0, v41
	v_add_f32_e32 v42, 1.0, v34
	v_add_f32_e32 v43, 1.0, v35
	v_add_f32_e32 v44, 1.0, v36
	v_add_f32_e32 v45, 1.0, v37
	v_rcp_f32_e32 v34, v38
	v_rcp_f32_e32 v35, v39
	v_rcp_f32_e32 v36, v40
	v_rcp_f32_e32 v37, v41
	v_rcp_f32_e32 v38, v42
	v_rcp_f32_e32 v39, v43
	v_rcp_f32_e32 v40, v44
	v_rcp_f32_e32 v41, v45
	v_pk_mul_f32 v[34:35], v[34:35], s[12:13] op_sel_hi:[1,0]
	v_pk_mul_f32 v[36:37], v[36:37], s[12:13] op_sel_hi:[1,0]
	v_pk_mul_f32 v[38:39], v[38:39], s[12:13] op_sel_hi:[1,0]
	v_pk_mul_f32 v[40:41], v[40:41], s[12:13] op_sel_hi:[1,0]
	v_cvt_pk_bf16_f32 v34, v34, v35
	v_cvt_pk_bf16_f32 v35, v36, v37
	v_cvt_pk_bf16_f32 v36, v38, v39
	v_cvt_pk_bf16_f32 v37, v40, v41
	v_lshl_add_u64 v[38:39], v[70:71], 1, v[50:51]
	global_store_dwordx4 v[38:39], v[34:37], off offset:64
; DI unsigned pack2(float a, float b) { f32x2_t v = {a, b}; bf16x2_t r = __builtin_convertvector(v, bf16x2_t); return __builtin_bit_cast(unsigned, r); }
; DI float sigmoidf_(float x) { return __builtin_amdgcn_rcpf(1.f + __builtin_amdgcn_exp2f(-1.4426950408889634f * x)); }
; template <class Epi>
; DI void gemm_small(const u16* __restrict__ A, int lda, const u16* __restrict__ Bt, int ldb, int N, int K, u16* __restrict__ O, int ldo, Epi epi,
;                    char* smem, int& rot) {
;     ...
; #pragma unroll
;     for (int mi = 0; mi < 4; ++mi) {
; #pragma unroll
;       for (int np = 0; np < 2; ++np) {
;         const int m = m0 + wm * 64 + mi * 16 + r16;
;         const int n = n0 + wn * 64 + np * 32 + quad * 8;
;         if (n < N) {
;           const f32x4 v0 = epi(n, acc[mi][2 * np]), v1 = epi(n + 4, acc[mi][2 * np + 1]);
;           uint4 o; o.x = pack2(v0[0], v0[1]); o.y = pack2(v0[2], v0[3]); o.z = pack2(v1[0], v1[1]); o.w = pack2(v1[2], v1[3]);
;           *(uint4*)(O + (size_t)m * ldo + n) = o;
;         }
;       }
;       __builtin_amdgcn_sched_barrier(0);
; __global__ void __launch_bounds__(512) fwd_megakernel(Params p) {
;     ...
;                      [=](int n, f32x4 v) {
;                        const float4 b = *(const float4*)(w0 + n);
;                        const float ce = 0.6065306597126334f;
;                        f32x4 o = {ce * sigmoidf_(v[0] + b.x), ce * sigmoidf_(v[1] + b.y), ce * sigmoidf_(v[2] + b.z), ce * sigmoidf_(v[3] + b.w)};
;                        return o;
.LBB0_1195:
	s_or_b64 exec, exec, s[36:37]
	s_nop 0
	v_or_b32_e32 v34, 32, v72
	v_ashrrev_i32_e32 v35, 31, v34
	v_lshlrev_b64 v[34:35], 10, v[34:35]
	v_lshl_add_u64 v[34:35], s[22:23], 0, v[34:35]
	s_and_saveexec_b64 s[36:37], vcc
	s_cbranch_execz .LBB0_1197
	v_add_f32_e32 v30, v30, v240
	v_add_f32_e32 v31, v31, v241
	v_add_f32_e32 v32, v32, v242
	v_add_f32_e32 v33, v33, v243
	v_add_f32_e32 v26, v26, v244
	v_add_f32_e32 v27, v27, v245
	v_add_f32_e32 v28, v28, v246
	v_add_f32_e32 v29, v29, v247
	v_mul_f32_e32 v30, 0xbfb8aa3b, v30
	v_mul_f32_e32 v31, 0xbfb8aa3b, v31
	v_mul_f32_e32 v32, 0xbfb8aa3b, v32
	v_mul_f32_e32 v33, 0xbfb8aa3b, v33
	v_mul_f32_e32 v26, 0xbfb8aa3b, v26
	v_mul_f32_e32 v27, 0xbfb8aa3b, v27
	v_mul_f32_e32 v28, 0xbfb8aa3b, v28
	v_mul_f32_e32 v29, 0xbfb8aa3b, v29
	v_exp_f32_e32 v30, v30
	v_exp_f32_e32 v31, v31
	v_exp_f32_e32 v32, v32
	v_exp_f32_e32 v33, v33
	v_exp_f32_e32 v26, v26
	v_exp_f32_e32 v27, v27
	v_exp_f32_e32 v28, v28
	v_exp_f32_e32 v29, v29
	v_add_f32_e32 v30, 1.0, v30
	v_add_f32_e32 v31, 1.0, v31
	v_add_f32_e32 v32, 1.0, v32
	v_add_f32_e32 v33, 1.0, v33
	v_add_f32_e32 v36, 1.0, v26
	v_add_f32_e32 v37, 1.0, v27
	v_add_f32_e32 v38, 1.0, v28
	v_add_f32_e32 v39, 1.0, v29
	v_rcp_f32_e32 v26, v30
	v_rcp_f32_e32 v27, v31
	v_rcp_f32_e32 v28, v32
	v_rcp_f32_e32 v29, v33
	v_rcp_f32_e32 v30, v36
	v_rcp_f32_e32 v31, v37
	v_rcp_f32_e32 v32, v38
	v_rcp_f32_e32 v33, v39
	v_pk_mul_f32 v[26:27], v[26:27], s[12:13] op_sel_hi:[1,0]
	v_pk_mul_f32 v[28:29], v[28:29], s[12:13] op_sel_hi:[1,0]
	v_pk_mul_f32 v[30:31], v[30:31], s[12:13] op_sel_hi:[1,0]
	v_pk_mul_f32 v[32:33], v[32:33], s[12:13] op_sel_hi:[1,0]
	v_cvt_pk_bf16_f32 v26, v26, v27
	v_cvt_pk_bf16_f32 v27, v28, v29
	v_cvt_pk_bf16_f32 v28, v30, v31
	v_cvt_pk_bf16_f32 v29, v32, v33
	v_lshl_add_u64 v[30:31], v[70:71], 1, v[34:35]
	global_store_dwordx4 v[30:31], v[26:29], off
.LBB0_1197:
	s_or_b64 exec, exec, s[36:37]
	s_and_saveexec_b64 s[36:37], s[0:1]
	s_cbranch_execz .LBB0_1199
	v_add_f32_e32 v22, v22, v248
	v_add_f32_e32 v23, v23, v249
	v_add_f32_e32 v24, v24, v250
	v_add_f32_e32 v25, v25, v251
	v_add_f32_e32 v18, v18, v252
	v_add_f32_e32 v19, v19, v253
	v_add_f32_e32 v20, v20, v254
	v_add_f32_e32 v21, v21, v255
	v_mul_f32_e32 v22, 0xbfb8aa3b, v22
	v_mul_f32_e32 v23, 0xbfb8aa3b, v23
	v_mul_f32_e32 v24, 0xbfb8aa3b, v24
	v_mul_f32_e32 v25, 0xbfb8aa3b, v25
	v_mul_f32_e32 v18, 0xbfb8aa3b, v18
	v_mul_f32_e32 v19, 0xbfb8aa3b, v19
	v_mul_f32_e32 v20, 0xbfb8aa3b, v20
	v_mul_f32_e32 v21, 0xbfb8aa3b, v21
	v_exp_f32_e32 v22, v22
	v_exp_f32_e32 v23, v23
	v_exp_f32_e32 v24, v24
	v_exp_f32_e32 v25, v25
	v_exp_f32_e32 v18, v18
	v_exp_f32_e32 v19, v19
	v_exp_f32_e32 v20, v20
	v_exp_f32_e32 v21, v21
	v_add_f32_e32 v22, 1.0, v22
	v_add_f32_e32 v23, 1.0, v23
	v_add_f32_e32 v24, 1.0, v24
	v_add_f32_e32 v25, 1.0, v25
	v_add_f32_e32 v26, 1.0, v18
	v_add_f32_e32 v27, 1.0, v19
	v_add_f32_e32 v28, 1.0, v20
	v_add_f32_e32 v29, 1.0, v21
	v_rcp_f32_e32 v18, v22
	v_rcp_f32_e32 v19, v23
	v_rcp_f32_e32 v20, v24
	v_rcp_f32_e32 v21, v25
	v_rcp_f32_e32 v22, v26
	v_rcp_f32_e32 v23, v27
	v_rcp_f32_e32 v24, v28
	v_rcp_f32_e32 v25, v29
	v_pk_mul_f32 v[18:19], v[18:19], s[12:13] op_sel_hi:[1,0]
	v_pk_mul_f32 v[20:21], v[20:21], s[12:13] op_sel_hi:[1,0]
	v_pk_mul_f32 v[22:23], v[22:23], s[12:13] op_sel_hi:[1,0]
	v_pk_mul_f32 v[24:25], v[24:25], s[12:13] op_sel_hi:[1,0]
	v_cvt_pk_bf16_f32 v18, v18, v19
	v_cvt_pk_bf16_f32 v19, v20, v21
	v_cvt_pk_bf16_f32 v20, v22, v23
	v_cvt_pk_bf16_f32 v21, v24, v25
	v_lshl_add_u64 v[22:23], v[70:71], 1, v[34:35]
	global_store_dwordx4 v[22:23], v[18:21], off offset:64
; DI unsigned pack2(float a, float b) { f32x2_t v = {a, b}; bf16x2_t r = __builtin_convertvector(v, bf16x2_t); return __builtin_bit_cast(unsigned, r); }
; DI float sigmoidf_(float x) { return __builtin_amdgcn_rcpf(1.f + __builtin_amdgcn_exp2f(-1.4426950408889634f * x)); }
; template <class Epi>
; DI void gemm_small(const u16* __restrict__ A, int lda, const u16* __restrict__ Bt, int ldb, int N, int K, u16* __restrict__ O, int ldo, Epi epi,
;                    char* smem, int& rot) {
;     ...
; #pragma unroll
;     for (int mi = 0; mi < 4; ++mi) {
; #pragma unroll
;       for (int np = 0; np < 2; ++np) {
;         const int m = m0 + wm * 64 + mi * 16 + r16;
;         const int n = n0 + wn * 64 + np * 32 + quad * 8;
;         if (n < N) {
;           const f32x4 v0 = epi(n, acc[mi][2 * np]), v1 = epi(n + 4, acc[mi][2 * np + 1]);
;           uint4 o; o.x = pack2(v0[0], v0[1]); o.y = pack2(v0[2], v0[3]); o.z = pack2(v1[0], v1[1]); o.w = pack2(v1[2], v1[3]);
;           *(uint4*)(O + (size_t)m * ldo + n) = o;
;         }
;       }
;       __builtin_amdgcn_sched_barrier(0);
; __global__ void __launch_bounds__(512) fwd_megakernel(Params p) {
;     ...
;                      [=](int n, f32x4 v) {
;                        const float4 b = *(const float4*)(w0 + n);
;                        const float ce = 0.6065306597126334f;
;                        f32x4 o = {ce * sigmoidf_(v[0] + b.x), ce * sigmoidf_(v[1] + b.y), ce * sigmoidf_(v[2] + b.z), ce * sigmoidf_(v[3] + b.w)};
;                        return o;
.LBB0_1199:
	s_or_b64 exec, exec, s[36:37]
	s_nop 0
	v_or_b32_e32 v18, 48, v72
	v_ashrrev_i32_e32 v19, 31, v18
	v_lshlrev_b64 v[18:19], 10, v[18:19]
	v_lshl_add_u64 v[18:19], s[22:23], 0, v[18:19]
	s_and_saveexec_b64 s[36:37], vcc
	s_cbranch_execz .LBB0_1201
	v_add_f32_e32 v14, v14, v240
	v_add_f32_e32 v15, v15, v241
	v_add_f32_e32 v16, v16, v242
	v_add_f32_e32 v17, v17, v243
	v_add_f32_e32 v10, v10, v244
	v_add_f32_e32 v11, v11, v245
	v_add_f32_e32 v12, v12, v246
	v_add_f32_e32 v13, v13, v247
	v_mul_f32_e32 v14, 0xbfb8aa3b, v14
	v_mul_f32_e32 v15, 0xbfb8aa3b, v15
	v_mul_f32_e32 v16, 0xbfb8aa3b, v16
	v_mul_f32_e32 v17, 0xbfb8aa3b, v17
	v_mul_f32_e32 v10, 0xbfb8aa3b, v10
	v_mul_f32_e32 v11, 0xbfb8aa3b, v11
	v_mul_f32_e32 v12, 0xbfb8aa3b, v12
	v_mul_f32_e32 v13, 0xbfb8aa3b, v13
	v_exp_f32_e32 v14, v14
	v_exp_f32_e32 v15, v15
	v_exp_f32_e32 v16, v16
	v_exp_f32_e32 v17, v17
	v_exp_f32_e32 v10, v10
	v_exp_f32_e32 v11, v11
	v_exp_f32_e32 v12, v12
	v_exp_f32_e32 v13, v13
	v_add_f32_e32 v14, 1.0, v14
	v_add_f32_e32 v15, 1.0, v15
	v_add_f32_e32 v16, 1.0, v16
	v_add_f32_e32 v17, 1.0, v17
	v_add_f32_e32 v20, 1.0, v10
	v_add_f32_e32 v21, 1.0, v11
	v_add_f32_e32 v22, 1.0, v12
	v_add_f32_e32 v23, 1.0, v13
	v_rcp_f32_e32 v10, v14
	v_rcp_f32_e32 v11, v15
	v_rcp_f32_e32 v12, v16
	v_rcp_f32_e32 v13, v17
	v_rcp_f32_e32 v14, v20
	v_rcp_f32_e32 v15, v21
	v_rcp_f32_e32 v16, v22
	v_rcp_f32_e32 v17, v23
	v_pk_mul_f32 v[10:11], v[10:11], s[12:13] op_sel_hi:[1,0]
	v_pk_mul_f32 v[12:13], v[12:13], s[12:13] op_sel_hi:[1,0]
	v_pk_mul_f32 v[14:15], v[14:15], s[12:13] op_sel_hi:[1,0]
	v_pk_mul_f32 v[16:17], v[16:17], s[12:13] op_sel_hi:[1,0]
	v_cvt_pk_bf16_f32 v10, v10, v11
	v_cvt_pk_bf16_f32 v11, v12, v13
	v_cvt_pk_bf16_f32 v12, v14, v15
	v_cvt_pk_bf16_f32 v13, v16, v17
	v_lshl_add_u64 v[14:15], v[70:71], 1, v[18:19]
	global_store_dwordx4 v[14:15], v[10:13], off
.LBB0_1201:
	s_or_b64 exec, exec, s[36:37]
	s_and_saveexec_b64 s[36:37], s[0:1]
	s_cbranch_execz .LBB0_1186
	v_add_f32_e32 v6, v6, v248
	v_add_f32_e32 v7, v7, v249
	v_add_f32_e32 v8, v8, v250
	v_add_f32_e32 v9, v9, v251
	v_add_f32_e32 v2, v2, v252
	v_add_f32_e32 v3, v3, v253
	v_add_f32_e32 v4, v4, v254
	v_add_f32_e32 v5, v5, v255
	v_mul_f32_e32 v6, 0xbfb8aa3b, v6
	v_mul_f32_e32 v7, 0xbfb8aa3b, v7
	v_mul_f32_e32 v8, 0xbfb8aa3b, v8
	v_mul_f32_e32 v9, 0xbfb8aa3b, v9
	v_mul_f32_e32 v2, 0xbfb8aa3b, v2
	v_mul_f32_e32 v3, 0xbfb8aa3b, v3
	v_mul_f32_e32 v4, 0xbfb8aa3b, v4
	v_mul_f32_e32 v5, 0xbfb8aa3b, v5
	v_exp_f32_e32 v6, v6
	v_exp_f32_e32 v7, v7
	v_exp_f32_e32 v8, v8
	v_exp_f32_e32 v9, v9
	v_exp_f32_e32 v2, v2
	v_exp_f32_e32 v3, v3
	v_exp_f32_e32 v4, v4
	v_exp_f32_e32 v5, v5
	v_add_f32_e32 v6, 1.0, v6
	v_add_f32_e32 v7, 1.0, v7
	v_add_f32_e32 v8, 1.0, v8
	v_add_f32_e32 v9, 1.0, v9
	v_add_f32_e32 v10, 1.0, v2
	v_add_f32_e32 v11, 1.0, v3
	v_add_f32_e32 v12, 1.0, v4
	v_add_f32_e32 v13, 1.0, v5
	v_rcp_f32_e32 v2, v6
	v_rcp_f32_e32 v3, v7
	v_rcp_f32_e32 v4, v8
	v_rcp_f32_e32 v5, v9
	v_rcp_f32_e32 v6, v10
	v_rcp_f32_e32 v7, v11
	v_rcp_f32_e32 v8, v12
	v_rcp_f32_e32 v9, v13
	v_pk_mul_f32 v[2:3], v[2:3], s[12:13] op_sel_hi:[1,0]
	v_pk_mul_f32 v[4:5], v[4:5], s[12:13] op_sel_hi:[1,0]
	v_pk_mul_f32 v[6:7], v[6:7], s[12:13] op_sel_hi:[1,0]
	v_pk_mul_f32 v[8:9], v[8:9], s[12:13] op_sel_hi:[1,0]
	v_cvt_pk_bf16_f32 v2, v2, v3
	v_cvt_pk_bf16_f32 v3, v4, v5
	v_cvt_pk_bf16_f32 v4, v6, v7
	v_cvt_pk_bf16_f32 v5, v8, v9
	v_lshl_add_u64 v[6:7], v[70:71], 1, v[18:19]
	global_store_dwordx4 v[6:7], v[2:5], off offset:64
	s_branch .LBB0_1186
